# attention work queue: every (batch, head, query-block) item queued singly in descending-size order (was pairs plus singles)
# speedup vs baseline: 1.1277x; 1.0137x over previous
; __device__ __forceinline__ int ltid() { return launder((int)threadIdx.x); }
; __device__ __forceinline__ void attn_phase(const Params& P, int layer) {
;     ...
;       __syncthreads();
;       if (ltid() == 0) *slot = (int)atomicAdd(ctl + 16 + layer * 8 + q, 1u);
;       __syncthreads();
;       const int idx = __builtin_amdgcn_readfirstlane(*slot);
;       if (idx >= N_PAIR) break;
;       const int p = idx & 15; int type, b, h, nh = 2, qs = -1;
;       if (idx < 32) { const int c2 = q + 8 * (idx >> 4); type = 1; b = c2 >> 2; h = c2 & 3; }
;       else if (idx < 64) { const int cm = q + 8 * ((idx - 32) >> 4); type = 0; b = cm / 6; h = cm % 6; }
;       else { const int cm = q + 16; type = 0; b = cm / 6; h = cm % 6; nh = 1; qs = 95 - idx; }
;       for (int half = 0; half < nh; ++half) { const int qb = nh == 1 ? qs : (half ? p : 31 - p); const int nm = type == 1 ? 2 : 1;
;         for (int mp = 0; mp < nm; ++mp) run_item(P, layer, type, b, h, mp, qb); }
.LBB0_1226:
	s_or_b64 exec, exec, s[2:3]
	v_mov_b32_e32 v0, s51
	s_waitcnt lgkmcnt(0)
	s_barrier
	ds_read_b32 v0, v0
	s_mov_b64 s[2:3], -1
	s_waitcnt lgkmcnt(0)
	v_readfirstlane_b32 s0, v0
	s_cmpk_gt_i32 s0, 0x9f
	s_cbranch_scc1 .LBB0_1221
	s_mov_b64 s[2:3], -1
	s_mov_b32 s79, 1
	v_writelane_b32 v255, s2, 3
	s_cmp_lt_i32 s0, 64
	v_writelane_b32 v255, s3, 4
	s_cselect_b64 s[8:9], -1, 0
	s_cbranch_scc0 .Lq_mla
	s_lshr_b32 s1, s0, 1
	s_sub_i32 s96, 31, s1
	s_and_b32 s1, s0, 1
	s_lshl_b32 s1, s1, 3
	v_readlane_b32 s2, v255, 0
	s_nop 3
	s_or_b32 s1, s1, s2
	s_ashr_i32 s85, s1, 2
	v_readlane_b32 s64, v254, 63
	s_mov_b32 s97, 2
	s_branch .LBB0_1235
.Lq_mla:
	s_sub_i32 s1, s0, 64
	s_mul_hi_u32 s2, s1, 0xaaaaaaab
	s_lshr_b32 s2, s2, 1
	s_sub_i32 s96, 31, s2
	s_mul_i32 s2, s2, 3
	s_sub_i32 s1, s1, s2
	s_lshl_b32 s1, s1, 3
	v_readlane_b32 s2, v255, 0
	s_nop 3
	s_or_b32 s1, s1, s2
	s_mul_hi_u32 s2, s1, 0xaaaaaaab
	s_lshr_b32 s85, s2, 2
	s_mul_i32 s2, s85, 6
	s_sub_i32 s64, s1, s2
	s_mov_b32 s97, 1
